# seam before FFN1-down panel-local too (write-through conversion stores + counter) on top of the split seams
# speedup vs baseline: 1.0004x; 1.0004x over previous
; #define LAS __attribute__((address_space(3)))
; #define SEAM(k) do { if (IN(k) && IN((k) + 1)) flat_barrier((unsigned*)(ws + WS_BAR + 65536), fgen, (unsigned)G); } while (0)
; #define SEAM(k) do { if (IN(k) && IN((k) + 1)) xcd_barrier(xbar); } while (0)
; __global__ void __launch_bounds__(NT, 2) hymba_fwd(Args args) {
;     ...
;         if (G == 256 && bx >= 160) p0_items(args, (LAS float*)(lds + wave * 16384), P0_EARLY, P0_MID, (bx - 160) * NWAVES + wave, 96 * NWAVES, lane);
;         else if (G != 256) p0_items(args, (LAS float*)(lds + wave * 16384), P0_EARLY, P0_MID, bx * NWAVES + wave, NGW, lane);
;     }
;     SEAM(1);
;     if (IN(2)) {
;         pg8::Gemm g{Hb, (const bf16*)(ws + WS_WD1), M, D, FF}; pg8::StaticOrder S; S.init(M, D, G, bx);
;         pg8::EpiResid E{nullptr  , XB, ssq + M, 0.5f, nullptr}; pg8::gemm_phase<pg8::EpiResid, pg8::StaticOrder, false, true>(lds, g, S, E);
;     }
;     SEAM(2);
.LBB0_292:
	s_cmp_gt_i32 s51, 2
	s_cselect_b64 s[4:5], -1, 0
	s_and_b64 s[6:7], s[14:15], s[4:5]
	s_andn2_b64 vcc, exec, s[6:7]
	s_cbranch_vccnz .LBB0_346
	v_mov_b32_e32 v1, 0x23fc8
	ds_read_b32 v2, v1
	s_waitcnt lgkmcnt(0)
	v_readfirstlane_b32 s14, v2
	s_cmp_lg_u32 s14, 1
	s_cbranch_scc1 .Lgb1_full
	s_waitcnt vmcnt(0)
	s_barrier
	s_cmp_eq_u64 s[44:45], 0
	s_cbranch_scc1 .Lgb1_gend
	s_mov_b64 s[8:9], exec
	s_mov_b64 exec, s[44:45]
	v_mov_b32_e32 v1, 1
	s_cmp_lt_u32 s2, 160
	s_cbranch_scc1 .Lgb1_gnoconv
	v_mov_b32_e32 v0, 0x8a00
	global_atomic_add v0, v1, s[46:47]

; __device__ __forceinline__ void panel_sync(unsigned* cnt, int pm, int wid, int lane) {
;     asm volatile("s_waitcnt vmcnt(0) lgkmcnt(0)" ::: "memory"); __builtin_amdgcn_s_barrier(); asm volatile("" ::: "memory");
;     if (wid == 0) {
;         if (lane == 0) { __builtin_amdgcn_fence(__ATOMIC_RELEASE, "agent"); asm volatile("s_waitcnt vmcnt(0)" ::: "memory"); __hip_atomic_fetch_add(cnt + 64 * pm, 1u, __ATOMIC_RELAXED, __HIP_MEMORY_SCOPE_AGENT); }
;         unsigned sp = 0;
;         while ((unsigned)__builtin_amdgcn_readfirstlane(__hip_atomic_load(cnt + 64 * pm, __ATOMIC_RELAXED, __HIP_MEMORY_SCOPE_AGENT)) < 4u) { __builtin_amdgcn_s_sleep(2); if (++sp > (1u << 22)) break; }
;         __builtin_amdgcn_fence(__ATOMIC_ACQUIRE, "agent");
;         asm volatile("s_waitcnt vmcnt(0)" ::: "memory");
;     }
;     asm volatile("" ::: "memory"); __builtin_amdgcn_s_barrier(); asm volatile("" ::: "memory");
; }
.Lgb2_gnolead:
	s_and_b32 s10, s2, 63
	s_lshl_b32 s10, s10, 8
	s_add_u32 s12, s46, s10
	s_addc_u32 s13, s47, 0
	v_mov_b32_e32 v0, 0xc000
	global_atomic_add v0, v1, s[12:13]
	s_mov_b32 s19, 0
.Lgb2_gpoll:
	global_load_dword v4, v0, s[12:13] sc1
	s_waitcnt vmcnt(0)
	v_readfirstlane_b32 s14, v4
	s_cmp_ge_u32 s14, 8
	s_cbranch_scc1 .Lgb2_gacq
	s_sleep 1
	s_add_i32 s19, s19, 1
	s_cmp_lt_u32 s19, 20000
	s_cbranch_scc1 .Lgb2_gpoll
.Lgb2_gacq:
	s_lshl_b32 s10, s33, 8
	s_add_i32 s10, s10, 0x10000
	v_mov_b32_e32 v5, s10
	global_load_dword v5, v5, s[46:47] sc1
	buffer_inv sc1
	s_waitcnt vmcnt(0)
	v_readfirstlane_b32 s14, v5
	s_cmp_ge_u32 s14, s101
	s_cselect_b32 s101, 0, s101
	s_mov_b64 exec, s[8:9]

; __device__ __forceinline__ void panel_sync(unsigned* cnt, int pm, int wid, int lane) {
;     asm volatile("s_waitcnt vmcnt(0) lgkmcnt(0)" ::: "memory"); __builtin_amdgcn_s_barrier(); asm volatile("" ::: "memory");
;     if (wid == 0) {
;         if (lane == 0) { __builtin_amdgcn_fence(__ATOMIC_RELEASE, "agent"); asm volatile("s_waitcnt vmcnt(0)" ::: "memory"); __hip_atomic_fetch_add(cnt + 64 * pm, 1u, __ATOMIC_RELAXED, __HIP_MEMORY_SCOPE_AGENT); }
;         unsigned sp = 0;
;         while ((unsigned)__builtin_amdgcn_readfirstlane(__hip_atomic_load(cnt + 64 * pm, __ATOMIC_RELAXED, __HIP_MEMORY_SCOPE_AGENT)) < 4u) { __builtin_amdgcn_s_sleep(2); if (++sp > (1u << 22)) break; }
;         __builtin_amdgcn_fence(__ATOMIC_ACQUIRE, "agent");
;         asm volatile("s_waitcnt vmcnt(0)" ::: "memory");
;     }
;     asm volatile("" ::: "memory"); __builtin_amdgcn_s_barrier(); asm volatile("" ::: "memory");
; }
.LBB0_1035:
	s_cmp_gt_i32 s51, 8
	s_cselect_b64 s[4:5], -1, 0
	s_and_b64 s[6:7], s[8:9], s[4:5]
	s_andn2_b64 vcc, exec, s[6:7]
	s_cbranch_vccnz .LBB0_1089
	v_mov_b32_e32 v1, 0x23fc8
	ds_read_b32 v2, v1
	s_waitcnt lgkmcnt(0)
	v_readfirstlane_b32 s14, v2
	s_cmp_lg_u32 s14, 1
	s_cbranch_scc1 .Lgb6_full
	s_waitcnt vmcnt(0)
	s_barrier
	s_cmp_eq_u64 s[44:45], 0
	s_cbranch_scc1 .Lgb6_gend
	s_mov_b64 s[8:9], exec
	s_mov_b64 exec, s[44:45]
	v_mov_b32_e32 v1, 1
	s_and_b32 s10, s2, 63
	s_lshl_b32 s10, s10, 8
	s_add_u32 s12, s46, s10
	s_addc_u32 s13, s47, 0
	v_mov_b32_e32 v0, 0xc000
	global_atomic_add v0, v1, s[12:13]
	s_mov_b32 s19, 0
.Lgb6_gpoll:
	global_load_dword v4, v0, s[12:13] sc1
	s_waitcnt vmcnt(0)
	v_readfirstlane_b32 s14, v4
	s_cmp_ge_u32 s14, 12
	s_cbranch_scc1 .Lgb6_gpanel
	s_sleep 1
	s_add_i32 s19, s19, 1
	s_cmp_lt_u32 s19, 20000
	s_cbranch_scc1 .Lgb6_gpoll

; __device__ __forceinline__ void panel_sync(unsigned* cnt, int pm, int wid, int lane) {
;     asm volatile("s_waitcnt vmcnt(0) lgkmcnt(0)" ::: "memory"); __builtin_amdgcn_s_barrier(); asm volatile("" ::: "memory");
;     if (wid == 0) {
;         if (lane == 0) { __builtin_amdgcn_fence(__ATOMIC_RELEASE, "agent"); asm volatile("s_waitcnt vmcnt(0)" ::: "memory"); __hip_atomic_fetch_add(cnt + 64 * pm, 1u, __ATOMIC_RELAXED, __HIP_MEMORY_SCOPE_AGENT); }
;         unsigned sp = 0;
;         while ((unsigned)__builtin_amdgcn_readfirstlane(__hip_atomic_load(cnt + 64 * pm, __ATOMIC_RELAXED, __HIP_MEMORY_SCOPE_AGENT)) < 4u) { __builtin_amdgcn_s_sleep(2); if (++sp > (1u << 22)) break; }
;         __builtin_amdgcn_fence(__ATOMIC_ACQUIRE, "agent");
;         asm volatile("s_waitcnt vmcnt(0)" ::: "memory");
;     }
;     asm volatile("" ::: "memory"); __builtin_amdgcn_s_barrier(); asm volatile("" ::: "memory");
; }
.LBB0_1111:
	s_cmp_gt_u32 s51, 9
	s_cselect_b64 s[4:5], -1, 0
	s_and_b64 s[4:5], s[8:9], s[4:5]
	s_andn2_b64 vcc, exec, s[4:5]
	s_cbranch_vccnz .LBB0_1165
	v_mov_b32_e32 v1, 0x23fc8
	ds_read_b32 v2, v1
	s_waitcnt lgkmcnt(0)
	v_readfirstlane_b32 s14, v2
	s_cmp_lg_u32 s14, 1
	s_cbranch_scc1 .Lgb7_full
	s_waitcnt vmcnt(0)
	s_barrier
	s_cmp_eq_u64 s[44:45], 0
	s_cbranch_scc1 .Lgb7_gend
	s_mov_b64 s[8:9], exec
	s_mov_b64 exec, s[44:45]
	v_mov_b32_e32 v1, 1
	s_and_b32 s10, s2, 63
	s_lshl_b32 s10, s10, 8
	s_add_u32 s12, s46, s10
	s_addc_u32 s13, s47, 0
	v_mov_b32_e32 v0, 0xc000
	global_atomic_add v0, v1, s[12:13]
	s_mov_b32 s19, 0
.Lgb7_gpoll:
	global_load_dword v4, v0, s[12:13] sc1
	s_waitcnt vmcnt(0)
	v_readfirstlane_b32 s14, v4
	s_cmp_ge_u32 s14, 16
	s_cbranch_scc1 .Lgb7_gpanel
	s_sleep 1
	s_add_i32 s19, s19, 1
	s_cmp_lt_u32 s19, 20000
	s_cbranch_scc1 .Lgb7_gpoll

; __device__ __forceinline__ void panel_sync(unsigned* cnt, int pm, int wid, int lane) {
;     asm volatile("s_waitcnt vmcnt(0) lgkmcnt(0)" ::: "memory"); __builtin_amdgcn_s_barrier(); asm volatile("" ::: "memory");
;     if (wid == 0) {
;         if (lane == 0) { __builtin_amdgcn_fence(__ATOMIC_RELEASE, "agent"); asm volatile("s_waitcnt vmcnt(0)" ::: "memory"); __hip_atomic_fetch_add(cnt + 64 * pm, 1u, __ATOMIC_RELAXED, __HIP_MEMORY_SCOPE_AGENT); }
;         unsigned sp = 0;
;         while ((unsigned)__builtin_amdgcn_readfirstlane(__hip_atomic_load(cnt + 64 * pm, __ATOMIC_RELAXED, __HIP_MEMORY_SCOPE_AGENT)) < 4u) { __builtin_amdgcn_s_sleep(2); if (++sp > (1u << 22)) break; }
;         __builtin_amdgcn_fence(__ATOMIC_ACQUIRE, "agent");
;         asm volatile("s_waitcnt vmcnt(0)" ::: "memory");
;     }
;     asm volatile("" ::: "memory"); __builtin_amdgcn_s_barrier(); asm volatile("" ::: "memory");
; }
.LBB0_1207:
	s_cmp_gt_i32 s51, 11
	s_cselect_b64 s[4:5], -1, 0
	s_and_b64 s[6:7], s[8:9], s[4:5]
	s_andn2_b64 vcc, exec, s[6:7]
	s_cbranch_vccnz .LBB0_1261
	v_mov_b32_e32 v1, 0x23fc8
	ds_read_b32 v2, v1
	s_waitcnt lgkmcnt(0)
	v_readfirstlane_b32 s14, v2
	s_cmp_lg_u32 s14, 1
	s_cbranch_scc1 .Lgb8_full
	s_waitcnt vmcnt(0)
	s_barrier
	s_cmp_eq_u64 s[44:45], 0
	s_cbranch_scc1 .Lgb8_gend
	s_mov_b64 s[8:9], exec
	s_mov_b64 exec, s[44:45]
	v_mov_b32_e32 v1, 1
	s_and_b32 s10, s2, 63
	s_lshl_b32 s10, s10, 8
	s_add_u32 s12, s46, s10
	s_addc_u32 s13, s47, 0
	v_mov_b32_e32 v0, 0xc000
	global_atomic_add v0, v1, s[12:13]
	s_mov_b32 s19, 0
.Lgb8_gpoll:
	global_load_dword v4, v0, s[12:13] sc1
	s_waitcnt vmcnt(0)
	v_readfirstlane_b32 s14, v4
	s_cmp_ge_u32 s14, 20
	s_cbranch_scc1 .Lgb8_gpanel
	s_sleep 1
	s_add_i32 s19, s19, 1
	s_cmp_lt_u32 s19, 20000
	s_cbranch_scc1 .Lgb8_gpoll
.Lgb8_gpanel:
.Lgb8_gacq:
	buffer_inv sc1
	s_waitcnt vmcnt(0)
	s_mov_b64 exec, s[8:9]
